# first grid barrier: the sixteen census counter loads are issued together and summed after one wait instead of one round trip each
# baseline (speedup 1.0000x reference)
; __device__ __forceinline__ unsigned xb_ld(unsigned* p)              { return __hip_atomic_load(p, __ATOMIC_RELAXED, __HIP_MEMORY_SCOPE_AGENT); }
; #define G opq(gridDim.x)
; #define c opq(blockIdx.x)
; __device__ __forceinline__ void xcd_barrier_complete(unsigned* bar, unsigned x, unsigned& nloc, unsigned& nx) {
;     ...
;     for (;;) {
;         sum = 0u; cnt = 0u; mine = 0u;
; #pragma unroll
;         for (unsigned j = 0; j < 16; ++j) { const unsigned c = xb_ld(&bar[XB_XCNT(j)]); sum += c; cnt += (c > 0u) ? 1u : 0u; mine = (j == x) ? c : mine; }
;         if (sum == G) break;
;         __builtin_amdgcn_s_sleep(1);
;         if ((++sp & 255u) == 0u) { if (xb_ld(&bar[XB_TMO])) break; if (sp > XB_SPIN_CAP) { atomicAdd(&bar[XB_TMO], 1u); break; } }
;     }
;     nloc = mine > 0u ? mine : 1u; nx = cnt > 0u ? cnt : 1u;
.LBB0_87:
	v_readlane_b32 s4, v254, 3
	v_readlane_b32 s5, v254, 4
	global_load_dword v2, v16, s[86:87] sc1
	s_waitcnt lgkmcnt(0)
	global_load_dword v0, v16, s[88:89] sc1
	global_load_dword v1, v16, s[56:57] sc1
	s_mov_b64 s[8:9], -1
	s_nop 0
	s_nop 0
	global_load_dword v3, v16, s[4:5] sc1
	v_readlane_b32 s4, v254, 5
	v_readlane_b32 s5, v254, 6
	s_nop 0
	s_nop 0
	s_nop 0
	s_nop 0
	s_nop 0
	global_load_dword v4, v16, s[4:5] sc1
	v_readlane_b32 s4, v254, 7
	v_readlane_b32 s5, v254, 8
	s_nop 0
	s_nop 0
	s_nop 2
	global_load_dword v5, v16, s[4:5] sc1
	v_readlane_b32 s4, v254, 9
	v_readlane_b32 s5, v254, 10
	s_nop 0
	s_nop 0
	s_nop 2
	global_load_dword v6, v16, s[4:5] sc1
	v_readlane_b32 s4, v254, 11
	v_readlane_b32 s5, v254, 12
	s_nop 0
	s_nop 0
	s_nop 2
	global_load_dword v7, v16, s[4:5] sc1
	v_readlane_b32 s4, v254, 13
	v_readlane_b32 s5, v254, 14
	s_nop 0
	s_nop 0
	s_nop 2
	global_load_dword v8, v16, s[4:5] sc1
	v_readlane_b32 s4, v254, 15
	v_readlane_b32 s5, v254, 16
	s_nop 0
	s_nop 0
	s_nop 2
	global_load_dword v9, v16, s[4:5] sc1
	v_readlane_b32 s4, v254, 17
	v_readlane_b32 s5, v254, 18
	s_nop 0
	s_nop 0
	s_nop 2
	global_load_dword v10, v16, s[4:5] sc1
	v_readlane_b32 s4, v254, 19
	v_readlane_b32 s5, v254, 20
	s_nop 0
	s_nop 0
	s_nop 2
	global_load_dword v11, v16, s[4:5] sc1
	v_readlane_b32 s4, v254, 21
	v_readlane_b32 s5, v254, 22
	s_nop 0
	s_nop 0
	s_nop 2
	global_load_dword v12, v16, s[4:5] sc1
	v_readlane_b32 s4, v254, 23
	v_readlane_b32 s5, v254, 24
	s_nop 0
	s_nop 0
	s_nop 2
	global_load_dword v13, v16, s[4:5] sc1
	v_readlane_b32 s4, v254, 25
	v_readlane_b32 s5, v254, 26
	s_nop 0
	s_nop 0
	s_nop 2
	global_load_dword v14, v16, s[4:5] sc1
	v_readlane_b32 s4, v254, 27
	v_readlane_b32 s5, v254, 28
	s_nop 0
	s_nop 0
	s_nop 2
	global_load_dword v15, v16, s[4:5] sc1
	s_mov_b64 s[4:5], -1
	s_waitcnt vmcnt(0)
	v_add_u32_e32 v17, v0, v2
	v_add_u32_e32 v17, v17, v1
	v_add_u32_e32 v17, v17, v3
	v_add_u32_e32 v17, v17, v4
	v_add_u32_e32 v17, v17, v5
	v_add_u32_e32 v17, v17, v6
	v_add_u32_e32 v17, v17, v7
	v_add_u32_e32 v17, v17, v8
	v_add_u32_e32 v17, v17, v9
	v_add_u32_e32 v17, v17, v10
	v_add_u32_e32 v17, v17, v11
	v_add_u32_e32 v17, v17, v12
	v_add_u32_e32 v17, v17, v13
	v_add_u32_e32 v17, v17, v14
	v_add_u32_e32 v17, v17, v15
	v_cmp_eq_u32_e32 vcc, s20, v17
	s_cbranch_vccnz .LBB0_86
	s_and_b32 s1, s0, 0xff
	s_cmp_eq_u32 s1, 0
	s_mov_b64 s[10:11], -1
	s_sleep 1
	s_cbranch_scc1 .LBB0_91
	s_and_b64 vcc, exec, s[10:11]
	s_cbranch_vccz .LBB0_86
